# code placement: attention loop start shifted by 4 bytes (one pad s_nop before the loop label, one after the loop)
# speedup vs baseline: 1.0110x; 1.0110x over previous
.Lat_nost2:
	s_nop 7
	s_nop 3
	v_max3_f32 v128, v48, v49, v50
	v_max3_f32 v128, v128, v51, v52
	v_max3_f32 v128, v128, v53, v54
	v_max3_f32 v128, v128, v55, v56
	v_max3_f32 v128, v128, v57, v58
	v_max3_f32 v128, v128, v59, v60
	v_max3_f32 v128, v128, v61, v62
	v_max3_f32 v128, v128, v63, v32
	v_max3_f32 v128, v128, v33, v34
	v_max3_f32 v128, v128, v35, v36
	v_max3_f32 v128, v128, v37, v38
	v_max3_f32 v128, v128, v39, v40
	v_max3_f32 v128, v128, v41, v42
	v_max3_f32 v128, v128, v43, v44
	v_max3_f32 v128, v128, v45, v46
	v_max_f32_e32 v128, v128, v47
	v_mov_b32_e32 v129, v128
	s_nop 1
	v_permlane32_swap_b32_e32 v128, v129
	v_max_f32_e32 v128, v128, v129
	v_sub_f32_e32 v168, 0, v128
	v_sub_f32_e32 v169, 0, v128
	v_sub_f32_e32 v170, 0, v128
	v_sub_f32_e32 v171, 0, v128
	v_sub_f32_e32 v172, 0, v128
	v_sub_f32_e32 v173, 0, v128
	v_sub_f32_e32 v174, 0, v128
	v_sub_f32_e32 v175, 0, v128
	v_sub_f32_e32 v176, 0, v128
	v_sub_f32_e32 v177, 0, v128
	v_sub_f32_e32 v178, 0, v128
	v_sub_f32_e32 v179, 0, v128
	v_sub_f32_e32 v180, 0, v128
	v_sub_f32_e32 v181, 0, v128
	v_sub_f32_e32 v182, 0, v128
	v_sub_f32_e32 v183, 0, v128
	v_sub_f32_e32 v48, v48, v128
	v_sub_f32_e32 v49, v49, v128
	v_sub_f32_e32 v50, v50, v128
	v_sub_f32_e32 v51, v51, v128
	v_sub_f32_e32 v52, v52, v128
	v_sub_f32_e32 v53, v53, v128
	v_sub_f32_e32 v54, v54, v128
	v_sub_f32_e32 v55, v55, v128
	v_sub_f32_e32 v56, v56, v128
	v_sub_f32_e32 v57, v57, v128
	v_sub_f32_e32 v58, v58, v128
	v_sub_f32_e32 v59, v59, v128
	v_sub_f32_e32 v60, v60, v128
	v_sub_f32_e32 v61, v61, v128
	v_sub_f32_e32 v62, v62, v128
	v_sub_f32_e32 v63, v63, v128
	v_sub_f32_e32 v32, v32, v128
	v_sub_f32_e32 v33, v33, v128
	v_sub_f32_e32 v34, v34, v128
	v_sub_f32_e32 v35, v35, v128
	v_sub_f32_e32 v36, v36, v128
	v_sub_f32_e32 v37, v37, v128
	v_sub_f32_e32 v38, v38, v128
	v_sub_f32_e32 v39, v39, v128
	v_sub_f32_e32 v40, v40, v128
	v_sub_f32_e32 v41, v41, v128
	v_sub_f32_e32 v42, v42, v128
	v_sub_f32_e32 v43, v43, v128
	v_sub_f32_e32 v44, v44, v128
	v_sub_f32_e32 v45, v45, v128
	v_sub_f32_e32 v46, v46, v128
	v_sub_f32_e32 v47, v47, v128
	v_exp_f32_e32 v48, v48
	v_exp_f32_e32 v49, v49
	v_exp_f32_e32 v50, v50
	v_exp_f32_e32 v51, v51
	v_exp_f32_e32 v52, v52
	v_exp_f32_e32 v53, v53
	v_exp_f32_e32 v54, v54
	v_exp_f32_e32 v55, v55
	v_exp_f32_e32 v56, v56
	v_exp_f32_e32 v57, v57
	v_exp_f32_e32 v58, v58
	v_exp_f32_e32 v59, v59
	v_exp_f32_e32 v60, v60
	v_exp_f32_e32 v61, v61
	v_exp_f32_e32 v62, v62
	v_exp_f32_e32 v63, v63
	v_cvt_pk_bf16_f32 v148, v48, v49
	v_cvt_pk_bf16_f32 v149, v50, v51
	v_cvt_pk_bf16_f32 v150, v52, v53
	v_cvt_pk_bf16_f32 v151, v54, v55
	v_cvt_pk_bf16_f32 v152, v56, v57
	v_cvt_pk_bf16_f32 v153, v58, v59
	v_cvt_pk_bf16_f32 v154, v60, v61
	v_cvt_pk_bf16_f32 v155, v62, v63
	v_add_u32_e32 v129, s82, v143
	v_add_u32_e32 v131, 0x1000, v129
	ds_read2_b64 v[184:187], v129 offset1:2
	ds_read2_b64 v[188:191], v131 offset0:32 offset1:34
	ds_read2_b64 v[192:195], v129 offset0:4 offset1:6
	ds_read2_b64 v[200:203], v131 offset0:36 offset1:38
	s_mov_b32 s86, s82
	s_mov_b32 s82, s83
	s_mov_b32 s83, s84
	s_mov_b32 s84, s86
	s_waitcnt lgkmcnt(4)
	s_barrier
	s_nop 0

.Lat_resc_back:
	s_cmpk_lt_u32 s35, 0x47
	s_waitcnt lgkmcnt(4)
	s_barrier
	s_cbranch_scc1 .Lat_loop
	s_nop 0
	s_waitcnt lgkmcnt(0)
	s_nop 7
	s_nop 7
	v_sub_f32_e32 v105, 0, v168
	v_mov_b32_e32 v98, v138
	s_branch .LBB0_105
